# LRU pass-1: next-tile gate-weight fragments prefetched into spare registers and consumed in place by the MFMAs (no copies), on top of the parameter-load hoist
# baseline (speedup 1.0000x reference)
; #define GAS __attribute__((address_space(1)))
; __device__ __forceinline__ int lru_pass1(const Params& P, int l, LAS unsigned char* lds, unsigned* qw) {
;     ...
;         for (int jt = 0; jt < 4; ++jt) { const int cl = 16 * jt + fr, c = h * 64 + cl;
;             f32x4 acc[4][4];
; #pragma unroll
;             for (int mt = 0; mt < 4; ++mt)
; #pragma unroll
;                 for (int dt = 0; dt < 4; ++dt) acc[mt][dt] = (f32x4){0.f, 0.f, 0.f, 0.f};
;             bf16x8 Bfr[4][2];
; #pragma unroll
;             for (int dt = 0; dt < 4; ++dt)
; #pragma unroll
;                 for (int kk = 0; kk < 2; ++kk) Bfr[dt][kk] = *(const GAS bf16x8*)(WGT + ((size_t)((dt * 8 + h) * 64 + cl)) * 64 + kk * 32 + 8 * fq);
;             __builtin_amdgcn_sched_barrier(0);
; #pragma unroll
;             for (int dt = 0; dt < 4; ++dt)
; #pragma unroll
;                 for (int kk = 0; kk < 2; ++kk) {
; #pragma unroll
;                     for (int mt = 0; mt < 4; ++mt) acc[mt][dt] = __builtin_amdgcn_mfma_f32_16x16x32_bf16(Af[mt][kk], Bfr[dt][kk], acc[mt][dt], 0, 0, 0); }
;             u32x2 abw[16];
; #pragma unroll
;             for (int d = 0; d < 2; ++d) {
;                 const float bgr = P.lru_bg[((l * 2 + d) * 2 + 0) * 512 + c], bgi = P.lru_bg[((l * 2 + d) * 2 + 1) * 512 + c];
;                 const float sp8 = SP8[(l * 2 + d) * 512 + c];
; #pragma unroll
;                 for (int mt = 0; mt < 4; ++mt)
; #pragma unroll
;                     for (int ip = 0; ip < 2; ++ip) { const int p = 16 * fq + 4 * mt + 2 * ip;
;                         const f32x2 xcv = (f32x2){bf2f(xcS[p * 72 + cl]), bf2f(xcS[(p + 1) * 72 + cl])};
;                         const f32x2 tr = ((f32x2){acc[mt][2 * d][2 * ip], acc[mt][2 * d][2 * ip + 1]} + bgr) * (-1.4426950408889634f);
;                         const f32x2 ti = ((f32x2){acc[mt][2 * d + 1][2 * ip], acc[mt][2 * d + 1][2 * ip + 1]} + bgi) * (-1.4426950408889634f);
;                         const f32x2 dr = (f32x2){__builtin_amdgcn_exp2f(tr.x), __builtin_amdgcn_exp2f(tr.y)} + 1.0f, di = (f32x2){__builtin_amdgcn_exp2f(ti.x), __builtin_amdgcn_exp2f(ti.y)} + 1.0f;
;                         const f32x2 r = (f32x2){__builtin_amdgcn_rcpf(dr.x), __builtin_amdgcn_rcpf(dr.y)}, ig = (f32x2){__builtin_amdgcn_rcpf(di.x), __builtin_amdgcn_rcpf(di.y)};
;                         const f32x2 la = r * (-sp8), x2 = la + la;
.LBB0_557:
	v_lshl_add_u64 v[54:55], v[154:155], 0, s[50:51]
	global_load_dword v218, v[54:55], off offset:-2048
	global_load_dword v219, v[54:55], off
	v_lshl_add_u64 v[54:55], s[92:93], 0, v[152:153]
	global_load_dword v220, v[54:55], off
	v_lshl_add_u64 v[54:55], v[150:151], 0, s[50:51]
	global_load_dword v221, v[54:55], off offset:-2048
	global_load_dword v222, v[54:55], off
	v_lshl_add_u64 v[54:55], s[92:93], 0, v[146:147]
	global_load_dword v223, v[54:55], off
	v_lshl_add_u64 v[52:53], s[92:93], 0, v[148:149]
	v_add_co_u32_e32 v52, vcc, 0x4e30000, v52
	s_nop 1
	v_addc_co_u32_e32 v53, vcc, 0, v53, vcc
	global_load_dwordx4 v[158:161], v[52:53], off
	global_load_dwordx4 v[162:165], v[52:53], off offset:64
	s_waitcnt vmcnt(8)
	s_nop 1
	s_waitcnt lgkmcnt(7)
	v_mfma_f32_16x16x32_bf16 v[52:55], v[0:3], v[224:227], 0
	s_waitcnt lgkmcnt(5)
	v_mfma_f32_16x16x32_bf16 v[60:63], v[8:11], v[224:227], 0
	s_waitcnt lgkmcnt(3)
	v_mfma_f32_16x16x32_bf16 v[64:67], v[16:19], v[224:227], 0
	s_waitcnt lgkmcnt(1)
	v_mfma_f32_16x16x32_bf16 v[32:35], v[24:27], v[224:227], 0
	v_mfma_f32_16x16x32_bf16 v[92:95], v[4:7], v[228:231], v[52:55]
	v_mfma_f32_16x16x32_bf16 v[84:87], v[12:15], v[228:231], v[60:63]
	v_mfma_f32_16x16x32_bf16 v[76:79], v[20:23], v[228:231], v[64:67]
	s_waitcnt lgkmcnt(0)
	v_mfma_f32_16x16x32_bf16 v[68:71], v[28:31], v[228:231], v[32:35]
	v_mfma_f32_16x16x32_bf16 v[32:35], v[0:3], v[232:235], 0
	v_mfma_f32_16x16x32_bf16 v[36:39], v[8:11], v[232:235], 0
	v_mfma_f32_16x16x32_bf16 v[52:55], v[16:19], v[232:235], 0
	v_mfma_f32_16x16x32_bf16 v[40:43], v[24:27], v[232:235], 0
	v_mfma_f32_16x16x32_bf16 v[88:91], v[4:7], v[236:239], v[32:35]
	v_mfma_f32_16x16x32_bf16 v[64:67], v[28:31], v[236:239], v[40:43]
	v_mfma_f32_16x16x32_bf16 v[32:35], v[0:3], v[240:243], 0
	v_mfma_f32_16x16x32_bf16 v[40:43], v[16:19], v[240:243], 0
	v_mfma_f32_16x16x32_bf16 v[80:83], v[12:15], v[236:239], v[36:39]
	v_mfma_f32_16x16x32_bf16 v[72:75], v[20:23], v[236:239], v[52:55]
	v_mfma_f32_16x16x32_bf16 v[36:39], v[8:11], v[240:243], 0
	v_mfma_f32_16x16x32_bf16 v[48:51], v[24:27], v[240:243], 0
	v_mfma_f32_16x16x32_bf16 v[60:63], v[4:7], v[244:247], v[32:35]
	v_mfma_f32_16x16x32_bf16 v[44:47], v[20:23], v[244:247], v[40:43]
	s_waitcnt vmcnt(1)
	v_mfma_f32_16x16x32_bf16 v[32:35], v[0:3], v[158:161], 0
	v_mfma_f32_16x16x32_bf16 v[40:43], v[8:11], v[158:161], 0
	v_mfma_f32_16x16x32_bf16 v[214:217], v[16:19], v[158:161], 0
	v_mfma_f32_16x16x32_bf16 v[158:161], v[24:27], v[158:161], 0
	v_mfma_f32_16x16x32_bf16 v[52:55], v[12:15], v[244:247], v[36:39]
	v_mfma_f32_16x16x32_bf16 v[36:39], v[28:31], v[244:247], v[48:51]
	s_waitcnt vmcnt(0)
	v_mfma_f32_16x16x32_bf16 v[56:59], v[4:7], v[162:165], v[32:35]
	v_mfma_f32_16x16x32_bf16 v[32:35], v[28:31], v[162:165], v[158:161]
	s_nop 2
	v_lshl_add_u64 v[158:159], v[154:155], 0, s[50:51]
	v_mov_b32_e32 v160, v218
	s_nop 0
	v_mov_b32_e32 v158, v219
	v_mfma_f32_16x16x32_bf16 v[48:51], v[12:15], v[162:165], v[40:43]
	s_waitcnt vmcnt(1)
	v_pk_add_f32 v[92:93], v[92:93], v[160:161] op_sel_hi:[1,0]
	v_mfma_f32_16x16x32_bf16 v[40:43], v[20:23], v[162:165], v[214:217]
	v_lshl_add_u64 v[162:163], s[92:93], 0, v[152:153]
	v_mov_b32_e32 v128, v220
	v_pk_mul_f32 v[92:93], v[92:93], s[18:19] op_sel_hi:[1,0]
	ds_read_u16 v159, v213
	ds_read_u16 v166, v213 offset:144
	v_exp_f32_e32 v92, v92
	v_exp_f32_e32 v93, v93
	s_nop 0
	v_pk_add_f32 v[92:93], v[92:93], 1.0 op_sel_hi:[1,0]
	s_nop 0
	v_rcp_f32_e32 v92, v92
	v_rcp_f32_e32 v93, v93
	s_waitcnt vmcnt(0)
	v_lshl_add_u64 v[162:163], s[92:93], 0, v[148:149]
	v_lshl_add_u64 v[162:163], v[162:163], 0, s[64:65]
	v_add_co_u32_e32 v162, vcc, 0x4e00000, v162
	s_nop 1
	v_addc_co_u32_e32 v163, vcc, 0, v163, vcc
	global_load_dwordx4 v[224:227], v[162:163], off
	global_load_dwordx4 v[228:231], v[162:163], off offset:64
	v_add_co_u32_e32 v162, vcc, 0x10000, v162
	s_nop 1
	v_addc_co_u32_e32 v163, vcc, 0, v163, vcc
	global_load_dwordx4 v[232:235], v[162:163], off
	global_load_dwordx4 v[236:239], v[162:163], off offset:64
	v_add_co_u32_e32 v162, vcc, 0x10000, v162
	s_nop 1
	v_addc_co_u32_e32 v163, vcc, 0, v163, vcc
	global_load_dwordx4 v[240:243], v[162:163], off
	global_load_dwordx4 v[244:247], v[162:163], off offset:64
	v_pk_mul_f32 v[92:93], v[128:129], v[92:93] op_sel_hi:[0,1] neg_lo:[1,0] neg_hi:[1,0]
	v_pk_add_f32 v[162:163], v[92:93], v[92:93]
	s_nop 0
	v_pk_fma_f32 v[164:165], v[162:163], s[20:21], v[136:137] op_sel_hi:[1,0,0]
	v_cmp_gt_f32_e64 s[46:47], s33, v162
	v_pk_fma_f32 v[164:165], v[162:163], v[164:165], s[22:23] op_sel_hi:[1,1,0]
	v_cmp_gt_f32_e64 s[44:45], s33, v163
	v_pk_fma_f32 v[164:165], v[162:163], v[164:165], 0.5 op_sel_hi:[1,1,0]
	s_or_b64 vcc, s[46:47], s[44:45]
	v_pk_fma_f32 v[164:165], v[162:163], v[164:165], 1.0 op_sel_hi:[1,1,0]
	s_nop 0
	v_pk_mul_f32 v[164:165], v[162:163], v[164:165] neg_lo:[0,1] neg_hi:[0,1]
	s_cbranch_vccnz .LBB0_577
